# v34: the P2 VALU trims (log range fix-ups removed, 5th scan step fused, decay broadcast via ds_bpermute) applied to the GLA prompt-item loop (.LBB0_632), which handles the 4096 prompt chunks
# baseline (speedup 1.0000x reference)
.LBB0_632:
	s_cmpk_lg_i32 s41, 0xc0
	s_waitcnt vmcnt(0)
	v_mov_b64_e32 v[42:43], v[38:39]
	s_cselect_b32 s60, s42, 48
	v_mov_b64_e32 v[40:41], v[36:37]
	v_mov_b64_e32 v[46:47], v[34:35]
	v_lshl_add_u64 v[36:37], s[60:61], 1, v[80:81]
	v_add_u32_e32 v75, s41, v56
	v_mov_b64_e32 v[44:45], v[32:33]
	global_load_dwordx4 v[32:35], v[36:37], off
	s_nop 0
	global_load_dwordx4 v[36:39], v[36:37], off offset:512
	ds_read_b128 v[48:51], v75 offset:16384
	ds_read_b128 v[52:55], v75 offset:16400
	ds_read_b128 v[188:191], v75
	ds_read_b128 v[192:195], v75 offset:16
	ds_read_b128 v[196:199], v75 offset:1024
	ds_read_b128 v[200:203], v75 offset:1040
	ds_read_b128 v[204:207], v75 offset:2048
	ds_read_b128 v[210:213], v75 offset:2064
	ds_read_b128 v[214:217], v75 offset:3072
	ds_read_b128 v[218:221], v75 offset:3088
	s_waitcnt lgkmcnt(7)
	v_pk_fma_f32 v[50:51], v[84:85], v[190:191], v[50:51]
	v_pk_fma_f32 v[48:49], v[82:83], v[188:189], v[48:49]
	s_waitcnt lgkmcnt(6)
	v_pk_fma_f32 v[54:55], v[84:85], v[194:195], v[54:55]
	v_pk_fma_f32 v[52:53], v[82:83], v[192:193], v[52:53]
	s_waitcnt lgkmcnt(5)
	v_pk_fma_f32 v[50:51], v[28:29], v[198:199], v[50:51]
	v_pk_fma_f32 v[48:49], v[86:87], v[196:197], v[48:49]
	s_waitcnt lgkmcnt(4)
	v_pk_fma_f32 v[54:55], v[28:29], v[202:203], v[54:55]
	v_pk_fma_f32 v[52:53], v[86:87], v[200:201], v[52:53]
	s_waitcnt lgkmcnt(3)
	v_pk_fma_f32 v[50:51], v[90:91], v[206:207], v[50:51]
	v_pk_fma_f32 v[48:49], v[88:89], v[204:205], v[48:49]
	s_waitcnt lgkmcnt(2)
	v_pk_fma_f32 v[54:55], v[90:91], v[212:213], v[54:55]
	v_pk_fma_f32 v[52:53], v[88:89], v[210:211], v[52:53]
	s_waitcnt lgkmcnt(1)
	v_pk_fma_f32 v[132:133], v[30:31], v[216:217], v[50:51]
	v_pk_fma_f32 v[214:215], v[92:93], v[214:215], v[48:49]
	s_waitcnt lgkmcnt(0)
	v_pk_fma_f32 v[216:217], v[30:31], v[220:221], v[54:55]
	v_pk_fma_f32 v[218:219], v[92:93], v[218:219], v[52:53]
	ds_read_b128 v[48:51], v75 offset:4096
	ds_read_b128 v[52:55], v75 offset:4112
	ds_read_b128 v[188:191], v75 offset:5120
	ds_read_b128 v[192:195], v75 offset:5136
	ds_read_b128 v[196:199], v75 offset:6144
	ds_read_b128 v[200:203], v75 offset:6160
	ds_read_b128 v[204:207], v75 offset:7168
	ds_read_b128 v[210:213], v75 offset:7184
	s_waitcnt lgkmcnt(7)
	v_pk_fma_f32 v[50:51], v[96:97], v[50:51], v[132:133]
	v_pk_fma_f32 v[48:49], v[94:95], v[48:49], v[214:215]
	s_waitcnt lgkmcnt(6)
	v_pk_fma_f32 v[54:55], v[96:97], v[54:55], v[216:217]
	v_pk_fma_f32 v[52:53], v[94:95], v[52:53], v[218:219]
	s_waitcnt lgkmcnt(5)
	v_pk_fma_f32 v[50:51], v[24:25], v[190:191], v[50:51]
	v_pk_fma_f32 v[48:49], v[98:99], v[188:189], v[48:49]
	s_waitcnt lgkmcnt(4)
	v_pk_fma_f32 v[54:55], v[24:25], v[194:195], v[54:55]
	v_pk_fma_f32 v[52:53], v[98:99], v[192:193], v[52:53]
	s_waitcnt lgkmcnt(3)
	v_pk_fma_f32 v[50:51], v[102:103], v[198:199], v[50:51]
	v_pk_fma_f32 v[48:49], v[100:101], v[196:197], v[48:49]
	s_waitcnt lgkmcnt(2)
	v_pk_fma_f32 v[54:55], v[102:103], v[202:203], v[54:55]
	v_pk_fma_f32 v[52:53], v[100:101], v[200:201], v[52:53]
	s_waitcnt lgkmcnt(1)
	v_pk_fma_f32 v[132:133], v[26:27], v[206:207], v[50:51]
	v_pk_fma_f32 v[214:215], v[104:105], v[204:205], v[48:49]
	s_waitcnt lgkmcnt(0)
	v_pk_fma_f32 v[216:217], v[26:27], v[212:213], v[54:55]
	v_pk_fma_f32 v[218:219], v[104:105], v[210:211], v[52:53]
	ds_read_b128 v[48:51], v75 offset:8192
	ds_read_b128 v[52:55], v75 offset:8208
	ds_read_b128 v[188:191], v75 offset:9216
	ds_read_b128 v[192:195], v75 offset:9232
	ds_read_b128 v[196:199], v75 offset:10240
	ds_read_b128 v[200:203], v75 offset:10256
	ds_read_b128 v[204:207], v75 offset:11264
	ds_read_b128 v[210:213], v75 offset:11280
	s_waitcnt lgkmcnt(7)
	v_pk_fma_f32 v[50:51], v[108:109], v[50:51], v[132:133]
	v_pk_fma_f32 v[48:49], v[106:107], v[48:49], v[214:215]
	s_waitcnt lgkmcnt(6)
	v_pk_fma_f32 v[54:55], v[108:109], v[54:55], v[216:217]
	v_pk_fma_f32 v[52:53], v[106:107], v[52:53], v[218:219]
	s_waitcnt lgkmcnt(5)
	v_pk_fma_f32 v[50:51], v[20:21], v[190:191], v[50:51]
	v_pk_fma_f32 v[48:49], v[110:111], v[188:189], v[48:49]
	s_waitcnt lgkmcnt(4)
	v_pk_fma_f32 v[54:55], v[20:21], v[194:195], v[54:55]
	v_pk_fma_f32 v[52:53], v[110:111], v[192:193], v[52:53]
	s_waitcnt lgkmcnt(3)
	v_pk_fma_f32 v[50:51], v[114:115], v[198:199], v[50:51]
	v_pk_fma_f32 v[48:49], v[112:113], v[196:197], v[48:49]
	s_waitcnt lgkmcnt(2)
	v_pk_fma_f32 v[54:55], v[114:115], v[202:203], v[54:55]
	v_pk_fma_f32 v[52:53], v[112:113], v[200:201], v[52:53]
	s_waitcnt lgkmcnt(1)
	v_pk_fma_f32 v[132:133], v[22:23], v[206:207], v[50:51]
	v_pk_fma_f32 v[214:215], v[116:117], v[204:205], v[48:49]
	s_waitcnt lgkmcnt(0)
	v_pk_fma_f32 v[216:217], v[22:23], v[212:213], v[54:55]
	v_pk_fma_f32 v[218:219], v[116:117], v[210:211], v[52:53]
	ds_read_b128 v[48:51], v75 offset:12288
	ds_read_b128 v[52:55], v75 offset:12304
	ds_read_b128 v[188:191], v75 offset:13312
	ds_read_b128 v[192:195], v75 offset:13328
	ds_read_b128 v[196:199], v75 offset:14336
	ds_read_b128 v[200:203], v75 offset:14352
	ds_read_b128 v[204:207], v75 offset:15360
	ds_read_b128 v[210:213], v75 offset:15376
	s_waitcnt lgkmcnt(7)
	v_pk_fma_f32 v[48:49], v[118:119], v[48:49], v[214:215]
	s_waitcnt lgkmcnt(6)
	v_pk_fma_f32 v[54:55], v[120:121], v[54:55], v[216:217]
	s_waitcnt lgkmcnt(5)
	v_pk_fma_f32 v[48:49], v[122:123], v[188:189], v[48:49]
	s_waitcnt lgkmcnt(4)
	v_pk_fma_f32 v[54:55], v[124:125], v[194:195], v[54:55]
	s_waitcnt lgkmcnt(3)
	v_pk_fma_f32 v[48:49], v[126:127], v[196:197], v[48:49]
	v_pk_fma_f32 v[50:51], v[120:121], v[50:51], v[132:133]
	s_waitcnt lgkmcnt(2)
	v_pk_fma_f32 v[132:133], v[128:129], v[202:203], v[54:55]
	s_waitcnt lgkmcnt(1)
	v_pk_fma_f32 v[54:55], v[130:131], v[204:205], v[48:49]
	v_pk_fma_f32 v[50:51], v[124:125], v[190:191], v[50:51]
	v_mul_f32_e64 v75, |v54|, s80
	v_exp_f32_e32 v75, v75
	v_mul_f32_e64 v77, |v55|, s80
	v_exp_f32_e32 v77, v77
	v_pk_fma_f32 v[52:53], v[118:119], v[52:53], v[218:219]
	v_add_f32_e32 v75, 1.0, v75
	v_add_f32_e32 v77, 1.0, v77
	v_pk_fma_f32 v[52:53], v[122:123], v[192:193], v[52:53]
	v_log_f32_e32 v75, v75
	v_pk_fma_f32 v[50:51], v[128:129], v[198:199], v[50:51]
	v_pk_fma_f32 v[188:189], v[126:127], v[200:201], v[52:53]
	v_pk_fma_f32 v[52:53], v[18:19], v[206:207], v[50:51]
	v_mul_f32_e32 v190, 0x3f317217, v75
	v_fma_f32 v190, v75, s10, -v190
	v_fmac_f32_e32 v190, 0x3377d1cf, v75
	v_fmac_f32_e32 v190, 0x3f317217, v75
	v_mul_f32_e64 v79, |v52|, s80
	v_exp_f32_e32 v79, v79
	v_mov_b32_e32 v75, v190
	v_add_f32_e32 v79, 1.0, v79
	v_log_f32_e32 v77, v77
	s_waitcnt lgkmcnt(0)
	v_pk_fma_f32 v[48:49], v[18:19], v[212:213], v[132:133]
	v_mul_f32_e64 v132, |v53|, s80
	v_exp_f32_e32 v132, v132
	v_mul_f32_e32 v190, 0x3f317217, v77
	v_fma_f32 v190, v77, s10, -v190
	v_fmac_f32_e32 v190, 0x3377d1cf, v77
	v_fmac_f32_e32 v190, 0x3f317217, v77
	v_add_f32_e32 v132, 1.0, v132
	v_pk_fma_f32 v[50:51], v[130:131], v[210:211], v[188:189]
	v_mov_b32_e32 v77, v190
	v_mul_f32_e64 v133, |v50|, s80
	v_log_f32_e32 v79, v79
	v_exp_f32_e32 v133, v133
	v_mul_f32_e64 v187, |v51|, s80
	v_exp_f32_e32 v187, v187
	v_mul_f32_e32 v190, 0x3f317217, v79
	v_fma_f32 v190, v79, s10, -v190
	v_fmac_f32_e32 v190, 0x3377d1cf, v79
	v_fmac_f32_e32 v190, 0x3f317217, v79
	v_add_f32_e32 v133, 1.0, v133
	v_add_f32_e32 v187, 1.0, v187
	v_mov_b32_e32 v79, v190
	v_mul_f32_e64 v188, |v48|, s80
	v_log_f32_e32 v132, v132
	v_exp_f32_e32 v188, v188
	v_mul_f32_e64 v189, |v49|, s80
	v_exp_f32_e32 v189, v189
	v_mul_f32_e32 v190, 0x3f317217, v132
	v_fma_f32 v190, v132, s10, -v190
	v_fmac_f32_e32 v190, 0x3377d1cf, v132
	v_fmac_f32_e32 v190, 0x3f317217, v132
	v_add_f32_e32 v188, 1.0, v188
	v_add_f32_e32 v189, 1.0, v189
	v_mov_b32_e32 v132, v190
	v_min_f32_e32 v54, 0, v54
	v_log_f32_e32 v133, v133
	v_sub_f32_e32 v54, v54, v75
	v_min_f32_e32 v55, 0, v55
	v_mul_f32_e32 v75, 0x3d800000, v54
	v_mul_f32_e32 v190, 0x3f317217, v133
	v_fma_f32 v190, v133, s10, -v190
	v_fmac_f32_e32 v190, 0x3377d1cf, v133
	v_fmac_f32_e32 v190, 0x3f317217, v133
	v_sub_f32_e32 v55, v55, v77
	v_min_f32_e32 v52, 0, v52
	v_mov_b32_e32 v133, v190
	v_mul_f32_e32 v77, 0x3d800000, v55
	v_log_f32_e32 v187, v187
	v_sub_f32_e32 v52, v52, v79
	v_min_f32_e32 v53, 0, v53
	v_mov_b32_dpp v75, v75 row_shr:1 row_mask:0xf bank_mask:0xf bound_ctrl:1
	v_mul_f32_e32 v190, 0x3f317217, v187
	v_fma_f32 v190, v187, s10, -v190
	v_fmac_f32_e32 v190, 0x3377d1cf, v187
	v_fmac_f32_e32 v190, 0x3f317217, v187
	v_mul_f32_e32 v79, 0x3d800000, v52
	v_sub_f32_e32 v53, v53, v132
	v_mov_b32_e32 v187, v190
	v_min_f32_e32 v50, 0, v50
	v_log_f32_e32 v188, v188
	v_fmac_f32_e32 v75, 0x3d800000, v54
	v_mov_b32_dpp v54, v77 row_shr:1 row_mask:0xf bank_mask:0xf bound_ctrl:1
	v_mul_f32_e32 v132, 0x3d800000, v53
	v_mul_f32_e32 v190, 0x3f317217, v188
	v_fma_f32 v190, v188, s10, -v190
	v_fmac_f32_e32 v190, 0x3377d1cf, v188
	v_fmac_f32_e32 v190, 0x3f317217, v188
	v_sub_f32_e32 v50, v50, v133
	v_min_f32_e32 v51, 0, v51
	v_mov_b32_e32 v188, v190
	v_fmac_f32_e32 v54, 0x3d800000, v55
	v_log_f32_e32 v189, v189
	v_mov_b32_dpp v55, v79 row_shr:1 row_mask:0xf bank_mask:0xf bound_ctrl:1
	v_mul_f32_e32 v133, 0x3d800000, v50
	v_sub_f32_e32 v51, v51, v187
	v_mul_f32_e32 v190, 0x3f317217, v189
	v_fma_f32 v190, v189, s10, -v190
	v_fmac_f32_e32 v190, 0x3377d1cf, v189
	v_fmac_f32_e32 v190, 0x3f317217, v189
	v_min_f32_e32 v48, 0, v48
	v_fmac_f32_e32 v55, 0x3d800000, v52
	v_mov_b32_dpp v52, v132 row_shr:1 row_mask:0xf bank_mask:0xf bound_ctrl:1
	v_mov_b32_e32 v189, v190
	v_mul_f32_e32 v187, 0x3d800000, v51
	v_sub_f32_e32 v48, v48, v188
	v_min_f32_e32 v49, 0, v49
	v_fmac_f32_e32 v52, 0x3d800000, v53
	v_mov_b32_dpp v53, v133 row_shr:1 row_mask:0xf bank_mask:0xf bound_ctrl:1
	v_mul_f32_e32 v188, 0x3d800000, v48
	v_sub_f32_e32 v49, v49, v189
	v_fmac_f32_e32 v53, 0x3d800000, v50
	v_mov_b32_dpp v50, v187 row_shr:1 row_mask:0xf bank_mask:0xf bound_ctrl:1
	v_mul_f32_e32 v189, 0x3d800000, v49
	v_fmac_f32_e32 v50, 0x3d800000, v51
	v_mov_b32_dpp v51, v188 row_shr:1 row_mask:0xf bank_mask:0xf bound_ctrl:1
	v_fmac_f32_e32 v51, 0x3d800000, v48
	v_mov_b32_dpp v48, v189 row_shr:1 row_mask:0xf bank_mask:0xf bound_ctrl:1
	v_fmac_f32_e32 v48, 0x3d800000, v49
	v_add_f32_dpp v49, v75, v75 row_shr:2 row_mask:0xf bank_mask:0xf bound_ctrl:1
	v_add_f32_dpp v54, v54, v54 row_shr:2 row_mask:0xf bank_mask:0xf bound_ctrl:1
	s_nop 0
	v_add_f32_dpp v49, v49, v49 row_shr:4 row_mask:0xf bank_mask:0xf bound_ctrl:1
	v_add_f32_dpp v54, v54, v54 row_shr:4 row_mask:0xf bank_mask:0xf bound_ctrl:1
	v_add_f32_dpp v55, v55, v55 row_shr:2 row_mask:0xf bank_mask:0xf bound_ctrl:1
	v_add_f32_dpp v49, v49, v49 row_shr:8 row_mask:0xf bank_mask:0xf bound_ctrl:1
	v_add_f32_dpp v54, v54, v54 row_shr:8 row_mask:0xf bank_mask:0xf bound_ctrl:1
	v_add_f32_dpp v55, v55, v55 row_shr:4 row_mask:0xf bank_mask:0xf bound_ctrl:1
	v_add_f32_dpp v49, v49, v49 row_bcast:15 row_mask:0xa bank_mask:0xf
	v_add_f32_dpp v52, v52, v52 row_shr:2 row_mask:0xf bank_mask:0xf bound_ctrl:1
	v_add_f32_dpp v55, v55, v55 row_shr:8 row_mask:0xf bank_mask:0xf bound_ctrl:1
	v_add_f32_dpp v54, v54, v54 row_bcast:15 row_mask:0xa bank_mask:0xf
	v_max_f32_e32 v49, 0xc2a00000, v49
	v_add_f32_dpp v52, v52, v52 row_shr:4 row_mask:0xf bank_mask:0xf bound_ctrl:1
	v_mul_f32_e32 v49, 0x3fb8aa3b, v49
	v_add_f32_dpp v53, v53, v53 row_shr:2 row_mask:0xf bank_mask:0xf bound_ctrl:1
	v_add_f32_dpp v52, v52, v52 row_shr:8 row_mask:0xf bank_mask:0xf bound_ctrl:1
	v_add_f32_dpp v55, v55, v55 row_bcast:15 row_mask:0xa bank_mask:0xf
	v_exp_f32_e32 v132, v49
	v_max_f32_e32 v49, 0xc2a00000, v54
	v_add_f32_dpp v53, v53, v53 row_shr:4 row_mask:0xf bank_mask:0xf bound_ctrl:1
	v_mul_f32_e32 v49, 0x3fb8aa3b, v49
	v_add_f32_dpp v50, v50, v50 row_shr:2 row_mask:0xf bank_mask:0xf bound_ctrl:1
	v_add_f32_dpp v53, v53, v53 row_shr:8 row_mask:0xf bank_mask:0xf bound_ctrl:1
	v_add_f32_dpp v52, v52, v52 row_bcast:15 row_mask:0xa bank_mask:0xf
	v_exp_f32_e32 v133, v49
	v_max_f32_e32 v49, 0xc2a00000, v55
	v_add_f32_dpp v50, v50, v50 row_shr:4 row_mask:0xf bank_mask:0xf bound_ctrl:1
	v_mul_f32_e32 v49, 0x3fb8aa3b, v49
	v_add_f32_dpp v51, v51, v51 row_shr:2 row_mask:0xf bank_mask:0xf bound_ctrl:1
	v_add_f32_dpp v50, v50, v50 row_shr:8 row_mask:0xf bank_mask:0xf bound_ctrl:1
	v_add_f32_dpp v53, v53, v53 row_bcast:15 row_mask:0xa bank_mask:0xf
	v_exp_f32_e32 v188, v49
	v_max_f32_e32 v49, 0xc2a00000, v52
	v_add_f32_dpp v51, v51, v51 row_shr:4 row_mask:0xf bank_mask:0xf bound_ctrl:1
	v_mul_f32_e32 v49, 0x3fb8aa3b, v49
	v_add_f32_dpp v48, v48, v48 row_shr:2 row_mask:0xf bank_mask:0xf bound_ctrl:1
	v_add_f32_dpp v51, v51, v51 row_shr:8 row_mask:0xf bank_mask:0xf bound_ctrl:1
	v_add_f32_dpp v50, v50, v50 row_bcast:15 row_mask:0xa bank_mask:0xf
	v_exp_f32_e32 v189, v49
	v_max_f32_e32 v49, 0xc2a00000, v53
	v_add_f32_dpp v48, v48, v48 row_shr:4 row_mask:0xf bank_mask:0xf bound_ctrl:1
	v_mul_f32_e32 v49, 0x3fb8aa3b, v49
	s_nop 0
	v_add_f32_dpp v48, v48, v48 row_shr:8 row_mask:0xf bank_mask:0xf bound_ctrl:1
	v_add_f32_dpp v51, v51, v51 row_bcast:15 row_mask:0xa bank_mask:0xf
	v_exp_f32_e32 v190, v49
	v_max_f32_e32 v49, 0xc2a00000, v50
	v_mul_f32_e32 v49, 0x3fb8aa3b, v49
	v_add_f32_dpp v48, v48, v48 row_bcast:15 row_mask:0xa bank_mask:0xf
	v_exp_f32_e32 v191, v49
	v_max_f32_e32 v49, 0xc2a00000, v51
	v_max_f32_e32 v48, 0xc2a00000, v48
	v_rcp_f32_e32 v196, v188
	v_rcp_f32_e32 v197, v189
	v_mul_f32_e32 v49, 0x3fb8aa3b, v49
	v_mul_f32_e32 v48, 0x3fb8aa3b, v48
	v_lshlrev_b32_e32 v202, 16, v44
	v_and_b32_e32 v203, 0xffff0000, v44
	v_exp_f32_e32 v192, v49
	v_exp_f32_e32 v193, v48
	ds_bpermute_b32 v48, v244, v132
	ds_bpermute_b32 v49, v244, v133
	ds_bpermute_b32 v50, v244, v188
	ds_bpermute_b32 v51, v244, v189
	ds_bpermute_b32 v52, v244, v190
	ds_bpermute_b32 v53, v244, v191
	ds_bpermute_b32 v54, v244, v192
	ds_bpermute_b32 v55, v244, v193
	v_pk_mul_f32 v[202:203], v[202:203], s[90:91] op_sel_hi:[1,0]
	v_lshlrev_b32_e32 v44, 16, v45
	v_and_b32_e32 v45, 0xffff0000, v45
	v_rcp_f32_e32 v194, v132
	v_rcp_f32_e32 v195, v133
	v_rcp_f32_e32 v198, v190
	v_rcp_f32_e32 v199, v191
	v_pk_mul_f32 v[132:133], v[202:203], v[132:133]
	v_lshlrev_b32_e32 v202, 16, v40
	v_and_b32_e32 v203, 0xffff0000, v40
	v_pk_mul_f32 v[44:45], v[44:45], s[90:91] op_sel_hi:[1,0]
	v_lshlrev_b32_e32 v40, 16, v41
	v_and_b32_e32 v41, 0xffff0000, v41
	v_pk_mul_f32 v[44:45], v[44:45], v[188:189]
	v_pk_mul_f32 v[188:189], v[196:197], v[40:41]
	v_lshlrev_b32_e32 v40, 16, v46
	v_and_b32_e32 v41, 0xffff0000, v46
	v_pk_mul_f32 v[40:41], v[40:41], s[90:91] op_sel_hi:[1,0]
	v_rcp_f32_e32 v200, v192
	v_rcp_f32_e32 v201, v193
	v_pk_mul_f32 v[190:191], v[40:41], v[190:191]
	v_lshlrev_b32_e32 v40, 16, v42
	v_and_b32_e32 v41, 0xffff0000, v42
	v_pk_mul_f32 v[196:197], v[198:199], v[40:41]
	v_lshlrev_b32_e32 v40, 16, v47
	v_and_b32_e32 v41, 0xffff0000, v47
	v_pk_mul_f32 v[40:41], v[40:41], s[90:91] op_sel_hi:[1,0]
	v_pk_mul_f32 v[46:47], v[40:41], v[192:193]
	v_lshlrev_b32_e32 v40, 16, v43
	v_and_b32_e32 v41, 0xffff0000, v43
	v_pk_mul_f32 v[194:195], v[194:195], v[202:203]
	v_pk_mul_f32 v[192:193], v[200:201], v[40:41]
	v_cvt_pk_bf16_f32 v41, v44, v45
	v_cvt_pk_bf16_f32 v43, v46, v47
	v_cvt_pk_bf16_f32 v44, v194, v195
	v_cvt_pk_bf16_f32 v45, v188, v189
	v_cvt_pk_bf16_f32 v46, v196, v197
	v_cvt_pk_bf16_f32 v47, v192, v193
	v_cvt_pk_bf16_f32 v40, v132, v133
	v_cvt_pk_bf16_f32 v42, v190, v191
	s_nop 1
	v_mfma_f32_32x32x16_bf16 v[2:17], v[44:47], v[40:43], v[2:17]
	s_waitcnt lgkmcnt(0)
	v_mul_f32_e32 v75, v194, v48
	v_mul_f32_e32 v77, v195, v49
	v_xor_b32_e32 v132, v71, v168
	v_mul_f32_e32 v79, v188, v50
	v_mul_f32_e32 v187, v189, v51
	v_lshl_add_u32 v132, v132, 4, v167
	v_cvt_pk_bf16_f32 v75, v75, v77
	v_mul_f32_e32 v198, v196, v52
	v_mul_f32_e32 v199, v197, v53
	ds_write_b128 v132, v[40:43] offset:20480
	ds_write_b16 v73, v75
	ds_write_b16_d16_hi v73, v75 offset:64
	v_cvt_pk_bf16_f32 v75, v79, v187
	v_mul_f32_e32 v200, v192, v54
	v_mul_f32_e32 v201, v193, v55
	ds_write_b16 v73, v75 offset:128
	ds_write_b16_d16_hi v73, v75 offset:192
	v_cvt_pk_bf16_f32 v75, v198, v199
	ds_write_b16 v73, v75 offset:256
	ds_write_b16_d16_hi v73, v75 offset:320
	v_cvt_pk_bf16_f32 v75, v200, v201
	ds_write_b16 v73, v75 offset:384
	ds_write_b16_d16_hi v73, v75 offset:448
	s_and_saveexec_b64 s[0:1], s[4:5]
	s_cbranch_execz .LBB0_631
	v_add_u32_e32 v40, s41, v183
	ds_write_b128 v40, v[48:51]
	ds_write_b128 v40, v[52:55] offset:16
	s_branch .LBB0_631
